# GLA scan: next-chunk q/k prefetch loads issued token by token inside section C's token loop right after each raw register's last use (no burst before the qe/ke barrier); one code path for both directi
# speedup vs baseline: 1.0112x; 1.0112x over previous
; __device__ __forceinline__ void scan_unit(const int unit, const Args& a, unsigned char* lds, const int mk_wid) {
;     ...
;     f32x16 S[4]; S[0] = f32x16{}; S[1] = f32x16{}; S[2] = f32x16{}; S[3] = f32x16{};
;     bf16x8 qraw[2], kraw[2], vraw[4]; bf16x8 lraw = bf16x8{};
.Lscan_cc_done:
	s_lshl_b32 s96, s96, 17
	s_lshl_b32 s97, s70, 12
	s_add_i32 s97, s97, 0xc800
	s_waitcnt vmcnt(0)
	s_cmp_lt_u32 s96, 0x80000
	s_cbranch_scc0 .Lscan_qkeep
	v_mov_b32_e32 v128, 0
	v_mov_b32_e32 v129, 0
	v_mov_b32_e32 v130, 0
	v_mov_b32_e32 v131, 0
	v_mov_b32_e32 v132, 0
	v_mov_b32_e32 v133, 0
	v_mov_b32_e32 v134, 0
	v_mov_b32_e32 v135, 0
.Lscan_qkeep:
.Lscan_nolrw:
	s_cmp_lt_i32 s34, 0
	s_cbranch_scc1 .Lscan_noflrd
	ds_read_b128 v[112:115], v253
	ds_read_b128 v[116:119], v253 offset:4096
	ds_read_b128 v[120:123], v253 offset:8192
	ds_read_b128 v[124:127], v253 offset:12288

.Lscan_nofl2:
	s_mov_b32 s99, 0
	s_cmp_eq_u32 s50, 3
	s_cbranch_scc1 .Lscan_pfi_have
	s_add_i32 s99, s5, 1
	s_bitcmp1_b32 s8, 0
	s_cbranch_scc0 .Lscan_pfi_have
	s_sub_i32 s99, 2, s5
	s_cmp_gt_u32 s5, 2
	s_cselect_b32 s99, s50, s99
.Lscan_pfi_have:
	s_lshl_b32 s98, s99, 12
	s_lshl_b32 s99, s99, 16
	s_bitcmp1_b32 s8, 0
	s_cbranch_scc0 .Lscan_pfi_fwd
	s_add_i32 s99, s99, 0x1c00
.Lscan_pfi_fwd:
	v_add_u32_e32 v68, s99, v245
	s_movk_i32 s99, 0x400
	s_bitcmp1_b32 s8, 0
	s_cbranch_scc0 .Lscan_pfi_fwd2
	s_movk_i32 s99, 0xfc00

; __device__ __forceinline__ int v_st(int k, int c) { const int kk = (k & ~0xC) | ((k & 4) << 1) | ((k & 8) >> 1); return ((kk >> 3) * 4 + (c >> 5)) * 512 + ((kk & 7) * 32 + (c & 31)) * 2; }
; __device__ __forceinline__ float bf2f(short s) { return __uint_as_float(((unsigned)(unsigned short)s) << 16); }
; __device__ __forceinline__ float bf2f(u16 u) { return __uint_as_float((unsigned)u << 16); }
; __device__ __forceinline__ u16 f2bf(float f) { return (u16)(pk2(f, 0.f) & 0xffffu); }
; __device__ __forceinline__ void scan_unit(const int unit, const Args& a, unsigned char* lds, const int mk_wid) {
;     ...
;           u16* qcol = qe + (g * 16) * QP + c; u16* kcol = ke + (g * 16) * QP + c; unsigned char* kdb = lds + L_KD + v_st(g * 16, c);
; #pragma unroll
;           for (int ii = 0; ii < 16; ++ii) { const float bb = bl[ii] + off;
;               const float qf = bf2f(qcol[ii * QP]), kf = bf2f(kcol[ii * QP]);
;               const float e = __builtin_amdgcn_exp2f(bb * 1.4426950408889634f), ker = kf * __builtin_amdgcn_rcpf(e);
;               qcol[ii * QP] = f2bf(qf * (0.088388347648318440f * e));
;               kcol[ii * QP] = f2bf(ker);
;               *(u16*)(kdb + v_st(ii, 0)) = f2bf(ker * dlc); } }
;         if (step + 1 < 36) GLA_LOAD(step + 1);
.Lscan_c2_nodl:
	v_mov_b32_e32 v71, 0xffff0000
	v_lshlrev_b32_e32 v218, 16, v128
	v_and_b32_e32 v219, v71, v128
	v_lshlrev_b32_e32 v220, 16, v100
	v_and_b32_e32 v221, v71, v100
	global_load_dword v100, v68, s[14:15]
	global_load_dword v128, v68, s[22:23]
	v_add_u32_e32 v68, s99, v68
	v_pk_mul_f32 v[218:219], v[170:171], v[218:219]
	v_pk_mul_f32 v[220:221], v[186:187], v[220:221]
	v_cvt_pk_bf16_f32 v224, v218, v219
	v_pk_mul_f32 v[222:223], v[92:93], v[220:221]
	v_cvt_pk_bf16_f32 v225, v220, v221
	ds_write_b32 v254, v224
	ds_write_b32 v254, v225 offset:17408
	v_cvt_pk_bf16_f32 v226, v222, v223
	ds_write_b32 v255, v226 offset:34816
	v_lshlrev_b32_e32 v228, 16, v129
	v_and_b32_e32 v229, v71, v129
	v_lshlrev_b32_e32 v230, 16, v101
	v_and_b32_e32 v231, v71, v101
	global_load_dword v101, v68, s[14:15]
	global_load_dword v129, v68, s[22:23]
	v_add_u32_e32 v68, s99, v68
	v_pk_mul_f32 v[228:229], v[172:173], v[228:229]
	v_pk_mul_f32 v[230:231], v[188:189], v[230:231]
	v_cvt_pk_bf16_f32 v234, v228, v229
	v_pk_mul_f32 v[232:233], v[92:93], v[230:231]
	v_cvt_pk_bf16_f32 v235, v230, v231
	ds_write_b32 v254, v234 offset:272
	ds_write_b32 v254, v235 offset:17680
	v_cvt_pk_bf16_f32 v236, v232, v233
	ds_write_b32 v255, v236 offset:34880
	v_lshlrev_b32_e32 v218, 16, v130
	v_and_b32_e32 v219, v71, v130
	v_lshlrev_b32_e32 v220, 16, v102
	v_and_b32_e32 v221, v71, v102
	global_load_dword v102, v68, s[14:15]
	global_load_dword v130, v68, s[22:23]
	v_add_u32_e32 v68, s99, v68
	v_pk_mul_f32 v[218:219], v[174:175], v[218:219]
	v_pk_mul_f32 v[220:221], v[190:191], v[220:221]
	v_cvt_pk_bf16_f32 v224, v218, v219
	v_pk_mul_f32 v[222:223], v[92:93], v[220:221]
	v_cvt_pk_bf16_f32 v225, v220, v221
	ds_write_b32 v254, v224 offset:544
	ds_write_b32 v254, v225 offset:17952
	v_cvt_pk_bf16_f32 v226, v222, v223
	ds_write_b32 v255, v226 offset:34944
	v_lshlrev_b32_e32 v228, 16, v131
	v_and_b32_e32 v229, v71, v131
	v_lshlrev_b32_e32 v230, 16, v103
	v_and_b32_e32 v231, v71, v103
	global_load_dword v103, v68, s[14:15]
	global_load_dword v131, v68, s[22:23]
	v_add_u32_e32 v68, s99, v68
	v_pk_mul_f32 v[228:229], v[176:177], v[228:229]
	v_pk_mul_f32 v[230:231], v[192:193], v[230:231]
	v_cvt_pk_bf16_f32 v234, v228, v229
	v_pk_mul_f32 v[232:233], v[92:93], v[230:231]
	v_cvt_pk_bf16_f32 v235, v230, v231
	ds_write_b32 v254, v234 offset:816
	ds_write_b32 v254, v235 offset:18224
	v_cvt_pk_bf16_f32 v236, v232, v233
	ds_write_b32 v255, v236 offset:35008
	v_lshlrev_b32_e32 v218, 16, v132
	v_and_b32_e32 v219, v71, v132
	v_lshlrev_b32_e32 v220, 16, v104
	v_and_b32_e32 v221, v71, v104
	global_load_dword v104, v68, s[14:15]
	global_load_dword v132, v68, s[22:23]
	v_add_u32_e32 v68, s99, v68
	v_pk_mul_f32 v[218:219], v[178:179], v[218:219]
	v_pk_mul_f32 v[220:221], v[194:195], v[220:221]
	v_cvt_pk_bf16_f32 v224, v218, v219
	v_pk_mul_f32 v[222:223], v[92:93], v[220:221]
	v_cvt_pk_bf16_f32 v225, v220, v221
	ds_write_b32 v254, v224 offset:1088
	ds_write_b32 v254, v225 offset:18496
	v_cvt_pk_bf16_f32 v226, v222, v223
	ds_write_b32 v255, v226 offset:36864
	v_lshlrev_b32_e32 v228, 16, v133
	v_and_b32_e32 v229, v71, v133
	v_lshlrev_b32_e32 v230, 16, v105
	v_and_b32_e32 v231, v71, v105
	global_load_dword v105, v68, s[14:15]
	global_load_dword v133, v68, s[22:23]
	v_add_u32_e32 v68, s99, v68
	v_pk_mul_f32 v[228:229], v[180:181], v[228:229]
	v_pk_mul_f32 v[230:231], v[196:197], v[230:231]
	v_cvt_pk_bf16_f32 v234, v228, v229
	v_pk_mul_f32 v[232:233], v[92:93], v[230:231]
	v_cvt_pk_bf16_f32 v235, v230, v231
	ds_write_b32 v254, v234 offset:1360
	ds_write_b32 v254, v235 offset:18768
	v_cvt_pk_bf16_f32 v236, v232, v233
	ds_write_b32 v255, v236 offset:36928
	v_lshlrev_b32_e32 v218, 16, v134
	v_and_b32_e32 v219, v71, v134
	v_lshlrev_b32_e32 v220, 16, v106
	v_and_b32_e32 v221, v71, v106
	global_load_dword v106, v68, s[14:15]
	global_load_dword v134, v68, s[22:23]
	v_add_u32_e32 v68, s99, v68
	v_pk_mul_f32 v[218:219], v[182:183], v[218:219]
	v_pk_mul_f32 v[220:221], v[198:199], v[220:221]
	v_cvt_pk_bf16_f32 v224, v218, v219
	v_pk_mul_f32 v[222:223], v[92:93], v[220:221]
	v_cvt_pk_bf16_f32 v225, v220, v221
	ds_write_b32 v254, v224 offset:1632
	ds_write_b32 v254, v225 offset:19040
	v_cvt_pk_bf16_f32 v226, v222, v223
	ds_write_b32 v255, v226 offset:36992
	v_lshlrev_b32_e32 v228, 16, v135
	v_and_b32_e32 v229, v71, v135
	v_lshlrev_b32_e32 v230, 16, v107
	v_and_b32_e32 v231, v71, v107
	global_load_dword v107, v68, s[14:15]
	global_load_dword v135, v68, s[22:23]
	v_pk_mul_f32 v[228:229], v[184:185], v[228:229]
	v_pk_mul_f32 v[230:231], v[200:201], v[230:231]
	v_cvt_pk_bf16_f32 v234, v228, v229
	v_pk_mul_f32 v[232:233], v[92:93], v[230:231]
	v_cvt_pk_bf16_f32 v235, v230, v231
	ds_write_b32 v254, v234 offset:1904
	ds_write_b32 v254, v235 offset:19312
	v_cvt_pk_bf16_f32 v236, v232, v233
	ds_write_b32 v255, v236 offset:37056
	v_add_u32_e32 v70, s98, v251
	v_mov_b32_e32 v71, 0
	v_lshl_add_u64 v[70:71], v[152:153], 0, v[70:71]
	global_load_dwordx4 v[96:99], v[70:71], off
	s_add_i32 s58, s5, 1
	s_cmp_lt_i32 s34, 0
	s_cbranch_scc1 .Lscan_vw_ns
	s_waitcnt vmcnt(21)
	s_branch .Lscan_vwd
.Lscan_vw_ns:
	s_waitcnt vmcnt(17)

; #define GLA_FLUSH() do { if (pend_cc >= 0) { OPAQUE_TID(tf_); const size_t rl0_ = (size_t)b * T + (size_t)(pend_cc - 4) * 64; \
;       _Pragma("unroll") for (int p = 0; p < 4; ++p) { const int idx_ = p * 512 + tf_, i_ = idx_ >> 5, c16_ = idx_ & 31; \
;           *(v4u*)(OUT + (rl0_ + (dir ? 63 - i_ : i_)) * 1024 + h * 256 + c16_ * 8) = *(const v4u*)(ot + i_ * 256 + c16_ * 8); } } } while (0)
; __device__ __forceinline__ void scan_unit(const int unit, const Args& a, unsigned char* lds, const int mk_wid) {
;     ...
;     GLA_FLUSH();
;     __syncthreads();
.LBB0_447:
	s_waitcnt vmcnt(0)
	s_and_b64 vcc, exec, s[26:27]
	s_cbranch_vccz .LBB0_449
	v_mbcnt_lo_u32_b32 v0, -1, 0
	v_mbcnt_hi_u32_b32 v0, -1, v0
	s_ashr_i32 s35, s34, 31
	v_add_u32_e32 v12, s72, v0
	s_lshl_b64 s[4:5], s[34:35], 6
	v_lshlrev_b32_e32 v0, 4, v12
	s_add_u32 s4, s4, s20
	v_and_b32_e32 v0, 0x1f0, v0
	v_ashrrev_i32_e32 v4, 5, v12
	s_addc_u32 s5, s5, s21
	v_add_u32_e32 v13, s9, v0
	v_mov_b32_e32 v1, 0
	v_sub_u32_e32 v5, 63, v4
	s_add_u32 s4, s4, 0xffffff00
	v_lshl_add_u64 v[8:9], s[18:19], 0, v[0:1]
	v_lshl_add_u32 v0, v4, 9, v13
	v_cndmask_b32_e64 v4, v5, v4, s[2:3]
	s_addc_u32 s5, s5, -1
	v_ashrrev_i32_e32 v5, 31, v4
	ds_read_b128 v[0:3], v0
	v_lshl_add_u64 v[4:5], s[4:5], 0, v[4:5]
	v_lshlrev_b64 v[4:5], 11, v[4:5]
	v_lshl_add_u64 v[10:11], v[8:9], 0, v[4:5]
	v_add_u32_e32 v4, 0x200, v12
	v_ashrrev_i32_e32 v14, 5, v4
	v_lshl_add_u32 v4, v14, 9, v13
	ds_read_b128 v[4:7], v4
	s_waitcnt lgkmcnt(1)
	global_store_dwordx4 v[10:11], v[0:3], off
	s_nop 1
	v_sub_u32_e32 v0, 63, v14
	v_cndmask_b32_e64 v0, v0, v14, s[2:3]
	v_ashrrev_i32_e32 v1, 31, v0
	v_lshl_add_u64 v[0:1], s[4:5], 0, v[0:1]
	v_lshlrev_b64 v[0:1], 11, v[0:1]
	v_lshl_add_u64 v[0:1], v[8:9], 0, v[0:1]
	s_waitcnt lgkmcnt(0)
	global_store_dwordx4 v[0:1], v[4:7], off
	v_add_u32_e32 v0, 0x400, v12
	s_nop 0
	v_ashrrev_i32_e32 v4, 5, v0
	v_sub_u32_e32 v5, 63, v4
	v_lshl_add_u32 v0, v4, 9, v13
	v_cndmask_b32_e64 v4, v5, v4, s[2:3]
	v_ashrrev_i32_e32 v5, 31, v4
	ds_read_b128 v[0:3], v0
	v_lshl_add_u64 v[4:5], s[4:5], 0, v[4:5]
	v_lshlrev_b64 v[4:5], 11, v[4:5]
	v_lshl_add_u64 v[10:11], v[8:9], 0, v[4:5]
	v_add_u32_e32 v4, 0x600, v12
	v_ashrrev_i32_e32 v12, 5, v4
	v_lshl_add_u32 v4, v12, 9, v13
	ds_read_b128 v[4:7], v4
	s_waitcnt lgkmcnt(1)
	global_store_dwordx4 v[10:11], v[0:3], off
	s_nop 1
	v_sub_u32_e32 v0, 63, v12
	v_cndmask_b32_e64 v0, v0, v12, s[2:3]
	v_ashrrev_i32_e32 v1, 31, v0
	v_lshl_add_u64 v[0:1], s[4:5], 0, v[0:1]
	v_lshlrev_b64 v[0:1], 11, v[0:1]
	v_lshl_add_u64 v[0:1], v[8:9], 0, v[0:1]
	s_waitcnt lgkmcnt(0)
	global_store_dwordx4 v[0:1], v[4:7], off
